# P5 epilogue: second-column-group conv weights fetched once at epilogue start (one quad per lane), parked in LDS and read back, removing the mid-epilogue global round trip; on top of v34
# speedup vs baseline: 1.0078x; 1.0060x over previous
;     __device__ __forceinline__ void operator()(AccT& acc, const Unit& u, int wr, int wc, int fr, int fq) const {
;         const int b = u.pm >> 6, tstart = (u.pm & 63) * 256;
;         const long arow0 = (long)u.pm * 256;
;         const int colg0 = u.pn * 128 + wc * 32 + fq * 8;
;         f32x4 cwg[2][3], cwv[2][3], cbg[2], cbv[2];
; #pragma unroll
;         for (int n = 0; n < 1; ++n) { const int colg = colg0 + n * 4, colv = FF + colg;
; #pragma unroll
;             for (int j = 0; j < 3; ++j) { cwg[n][j] = *(const f32x4*)(cw + j * FF2 + colg); cwv[n][j] = *(const f32x4*)(cw + j * FF2 + colv); }
;             cbg[n] = *(const f32x4*)(cb + colg); cbv[n] = *(const f32x4*)(cb + colv); }
;         float sq[2][4];
; #pragma unroll
;         for (int ai = 0; ai < 2; ++ai)
; #pragma unroll
;             for (int m = 0; m < 4; ++m) { const int rl = ai * 128 + wr * 64 + m * 16 + fr, t = tstart + rl; sq[ai][m] = ssq[arow0 + rl]; }
;     ...
;                 for (int j = 0; j < 3; ++j) { cwg[1][j] = *(const f32x4*)(cw + j * FF2 + colg); cwv[1][j] = *(const f32x4*)(cw + j * FF2 + colv); }
;                 cbg[1] = *(const f32x4*)(cb + colg); cbv[1] = *(const f32x4*)(cb + colv); }
.LBB0_1028:
	s_lshl_b32 s3, s22, 7
	v_readlane_b32 s9, v246, 38
	s_ashr_i32 s17, s16, 31
	v_readlane_b32 s18, v246, 20
	v_readlane_b32 s19, v246, 21
	v_readlane_b32 s20, v246, 30
	s_or_b32 s3, s3, s9
	v_lshlrev_b32_e32 v182, 3, v230
	v_mov_b32_e32 v183, 0
	v_mov_b32_e32 v193, 0
	v_add_u32_e32 v182, s3, v182
	s_lshl_b64 s[14:15], s[16:17], 10
	v_lshl_add_u32 v192, v229, 2, s20
	s_add_u32 s14, s18, s14
	s_addc_u32 s15, s19, s15
	v_lshl_add_u64 v[126:127], v[192:193], 2, s[14:15]
	global_load_dword v206, v[126:127], off
	global_load_dword v207, v[126:127], off offset:4
	global_load_dword v208, v[126:127], off offset:8
	global_load_dword v209, v[126:127], off offset:12
	global_load_dword v210, v[126:127], off offset:512
	global_load_dword v211, v[126:127], off offset:516
	global_load_dword v212, v[126:127], off offset:520
	global_load_dword v213, v[126:127], off offset:524
	v_cmp_eq_u32_e64 s[48:49], 0, v229
	v_cmp_eq_u32_e64 s[50:51], 15, v229
	s_cmp_eq_u32 s20, 0
	s_cselect_b64 s[54:55], -1, 0
	s_cselect_b64 s[72:73], 0, -1
	s_mov_b64 s[52:53], 0x2000
	s_and_b64 s[74:75], s[48:49], s[54:55]
	s_and_b64 s[76:77], s[50:51], s[72:73]
	s_and_b64 s[80:81], s[48:49], s[72:73]
	v_lshlrev_b64 v[126:127], 2, v[182:183]
	v_lshl_add_u64 v[214:215], s[44:45], 0, v[126:127]
	global_load_dwordx4 v[98:101], v[214:215], off
	v_lshl_add_u64 v[214:215], v[214:215], 0, s[52:53]
	global_load_dwordx4 v[84:87], v[214:215], off offset:3072
	v_lshl_add_u64 v[214:215], s[40:41], 0, v[126:127]
	global_load_dwordx4 v[102:105], v[214:215], off
	v_lshl_add_u64 v[214:215], v[214:215], 0, s[52:53]
	global_load_dwordx4 v[92:95], v[214:215], off offset:3072
	v_lshl_add_u64 v[214:215], s[42:43], 0, v[126:127]
	global_load_dwordx4 v[106:109], v[214:215], off
	v_lshl_add_u64 v[214:215], v[214:215], 0, s[52:53]
	global_load_dwordx4 v[88:91], v[214:215], off offset:3072
	v_lshl_add_u64 v[214:215], s[94:95], 0, v[126:127]
	global_load_dwordx4 v[110:113], v[214:215], off
	v_lshl_add_u64 v[214:215], v[214:215], 0, s[52:53]
	global_load_dwordx4 v[80:83], v[214:215], off offset:3072
	s_lshl_b64 s[16:17], s[16:17], 8
	v_lshl_add_u64 v[184:185], s[16:17], 0, v[192:193]
	v_mov_b64_e32 v[216:217], s[84:85]
	s_movk_i32 s3, 0x1600
	v_mad_u64_u32 v[216:217], s[22:23], v184, s3, v[216:217]
	v_mad_i32_i24 v217, v185, s3, v217
	v_lshl_add_u64 v[184:185], v[182:183], 1, v[216:217]
	s_mov_b32 s56, 0
	s_mov_b32 s57, 0
	s_mov_b32 s58, 5632
	s_mov_b32 s59, 0
	s_mov_b32 s60, 11264
	s_mov_b32 s61, 0
	s_mov_b32 s62, 16896
	s_mov_b32 s63, 0
	s_mov_b32 s64, 720896
	s_mov_b32 s65, 0
	s_mov_b32 s66, 726528
	s_mov_b32 s67, 0
	s_mov_b32 s68, 732160
	s_mov_b32 s69, 0
	s_mov_b32 s70, 737792
	s_mov_b32 s71, 0
	s_lshl_b32 s3, s20, 5
	s_lshl_b32 s9, s9, 4
	s_add_i32 s3, s3, s9
	s_add_i32 s3, s3, 0x20000
	v_lshl_add_u32 v189, v230, 7, s3
	s_add_i32 s9, s9, 0x22000
	v_lshl_add_u32 v255, v230, 7, s9
	v_and_b32_e32 v254, 7, v229
	v_lshl_add_u32 v254, v254, 4, v255
	v_and_b32_e32 v220, 3, v229
	v_max_u32_e32 v221, 1, v220
	v_add_u32_e32 v221, 0xffffffff, v221
	v_mov_b64_e32 v[218:219], s[40:41]
	s_movk_i32 s3, 0x5800
	v_mad_u64_u32 v[218:219], s[22:23], v221, s3, v[218:219]
	v_mov_b64_e32 v[214:215], s[44:45]
	v_cmp_eq_u32_e64 s[22:23], 0, v220
	s_nop 1
	v_cndmask_b32_e64 v218, v218, v214, s[22:23]
	v_cndmask_b32_e64 v219, v219, v215, s[22:23]
	v_bfe_u32 v220, v229, 2, 1
	v_mul_u32_u24_e32 v220, 0x2c00, v220
	v_lshl_add_u32 v220, v182, 2, v220
	v_mov_b32_e32 v221, 0
	v_lshl_add_u64 v[218:219], v[218:219], 0, v[220:221]
	global_load_dwordx4 v[214:217], v[218:219], off offset:16
	v_add_u32_e32 v188, 0xfffff800, v189
	v_mov_b32_e32 v186, 0xbf3a00e3
	s_waitcnt vmcnt(0)
; #define LAS __attribute__((address_space(3)))
;     __device__ __forceinline__ void operator()(AccT& acc, const Unit& u, int wr, int wc, int fr, int fq) const {
;     ...
; #pragma unroll
;         for (int ai = 0; ai < 2; ++ai)
; #pragma unroll
;             for (int m = 0; m < 4; ++m) {
;                 const int rl = ai * 128 + wr * 64 + m * 16 + fr;
;                 const int t = tstart + rl;
;                 const float rs = __builtin_amdgcn_rsqf(sq[ai][m] * (1.0f / 1024.0f) + EPS);
; #pragma unroll
;                 for (int bj = 0; bj < 2; ++bj)
; #pragma unroll
;                     for (int n = 0; n < 2; ++n) acc[ai][bj][m][n] = acc[ai][bj][m][n] * rs;
;             }
;         if (fr >= 14) {
; #pragma unroll
;             for (int ai = 0; ai < 2; ++ai)
; #pragma unroll
;                 for (int bj = 0; bj < 2; ++bj)
; #pragma unroll
;                     for (int n = 0; n < 2; ++n)
;                         *(LAS f32x4*)(xch + (((ai * 2 + wr) * 2 + (fr - 14)) * 256 + bj * 128 + wc * 32 + fq * 8 + n * 4)) = acc[ai][bj][3][n];
;         }
	ds_write_b128 v254, v[214:217]
	s_nop 1
	v_fmamk_f32 v126, v206, 0x3a800000, v223
	v_rsq_f32_e32 v126, v126
	s_nop 0
	v_pk_mul_f32 v[160:161], v[160:161], v[126:127] op_sel_hi:[1,0]
	v_pk_mul_f32 v[162:163], v[162:163], v[126:127] op_sel_hi:[1,0]
	v_pk_mul_f32 v[60:61], v[60:61], v[126:127] op_sel_hi:[1,0]
	v_pk_mul_f32 v[62:63], v[62:63], v[126:127] op_sel_hi:[1,0]
	v_pk_mul_f32 v[156:157], v[156:157], v[126:127] op_sel_hi:[1,0]
	v_pk_mul_f32 v[158:159], v[158:159], v[126:127] op_sel_hi:[1,0]
	v_pk_mul_f32 v[56:57], v[56:57], v[126:127] op_sel_hi:[1,0]
	v_pk_mul_f32 v[58:59], v[58:59], v[126:127] op_sel_hi:[1,0]
	v_fmamk_f32 v126, v207, 0x3a800000, v223
	v_rsq_f32_e32 v126, v126
	s_nop 0
	v_pk_mul_f32 v[144:145], v[144:145], v[126:127] op_sel_hi:[1,0]
	v_pk_mul_f32 v[146:147], v[146:147], v[126:127] op_sel_hi:[1,0]
	v_pk_mul_f32 v[52:53], v[52:53], v[126:127] op_sel_hi:[1,0]
	v_pk_mul_f32 v[54:55], v[54:55], v[126:127] op_sel_hi:[1,0]
	v_pk_mul_f32 v[118:119], v[118:119], v[126:127] op_sel_hi:[1,0]
	v_pk_mul_f32 v[120:121], v[120:121], v[126:127] op_sel_hi:[1,0]
	v_pk_mul_f32 v[40:41], v[40:41], v[126:127] op_sel_hi:[1,0]
	v_pk_mul_f32 v[42:43], v[42:43], v[126:127] op_sel_hi:[1,0]
	v_fmamk_f32 v126, v208, 0x3a800000, v223
	v_rsq_f32_e32 v126, v126
	s_nop 0
	v_pk_mul_f32 v[140:141], v[140:141], v[126:127] op_sel_hi:[1,0]
	v_pk_mul_f32 v[142:143], v[142:143], v[126:127] op_sel_hi:[1,0]
	v_pk_mul_f32 v[36:37], v[36:37], v[126:127] op_sel_hi:[1,0]
	v_pk_mul_f32 v[38:39], v[38:39], v[126:127] op_sel_hi:[1,0]
	v_pk_mul_f32 v[114:115], v[114:115], v[126:127] op_sel_hi:[1,0]
	v_pk_mul_f32 v[116:117], v[116:117], v[126:127] op_sel_hi:[1,0]
	v_pk_mul_f32 v[32:33], v[32:33], v[126:127] op_sel_hi:[1,0]
	v_pk_mul_f32 v[34:35], v[34:35], v[126:127] op_sel_hi:[1,0]
	v_fmamk_f32 v126, v209, 0x3a800000, v223
	v_rsq_f32_e32 v126, v126
	s_nop 0
	v_pk_mul_f32 v[152:153], v[152:153], v[126:127] op_sel_hi:[1,0]
	v_pk_mul_f32 v[154:155], v[154:155], v[126:127] op_sel_hi:[1,0]
	v_pk_mul_f32 v[48:49], v[48:49], v[126:127] op_sel_hi:[1,0]
	v_pk_mul_f32 v[50:51], v[50:51], v[126:127] op_sel_hi:[1,0]
	v_pk_mul_f32 v[148:149], v[148:149], v[126:127] op_sel_hi:[1,0]
	v_pk_mul_f32 v[150:151], v[150:151], v[126:127] op_sel_hi:[1,0]
	v_pk_mul_f32 v[44:45], v[44:45], v[126:127] op_sel_hi:[1,0]
	v_pk_mul_f32 v[46:47], v[46:47], v[126:127] op_sel_hi:[1,0]
	v_fmamk_f32 v126, v210, 0x3a800000, v223
	v_rsq_f32_e32 v126, v126
	s_nop 0
	v_pk_mul_f32 v[136:137], v[136:137], v[126:127] op_sel_hi:[1,0]
	v_pk_mul_f32 v[138:139], v[138:139], v[126:127] op_sel_hi:[1,0]
	v_pk_mul_f32 v[28:29], v[28:29], v[126:127] op_sel_hi:[1,0]
	v_pk_mul_f32 v[30:31], v[30:31], v[126:127] op_sel_hi:[1,0]
	v_pk_mul_f32 v[132:133], v[132:133], v[126:127] op_sel_hi:[1,0]
	v_pk_mul_f32 v[134:135], v[134:135], v[126:127] op_sel_hi:[1,0]
	v_pk_mul_f32 v[24:25], v[24:25], v[126:127] op_sel_hi:[1,0]
	v_pk_mul_f32 v[26:27], v[26:27], v[126:127] op_sel_hi:[1,0]
	v_fmamk_f32 v126, v211, 0x3a800000, v223
	v_rsq_f32_e32 v126, v126
	s_nop 0
	v_pk_mul_f32 v[76:77], v[76:77], v[126:127] op_sel_hi:[1,0]
	v_pk_mul_f32 v[78:79], v[78:79], v[126:127] op_sel_hi:[1,0]
	v_pk_mul_f32 v[12:13], v[12:13], v[126:127] op_sel_hi:[1,0]
	v_pk_mul_f32 v[14:15], v[14:15], v[126:127] op_sel_hi:[1,0]
	v_pk_mul_f32 v[72:73], v[72:73], v[126:127] op_sel_hi:[1,0]
	v_pk_mul_f32 v[74:75], v[74:75], v[126:127] op_sel_hi:[1,0]
	v_pk_mul_f32 v[8:9], v[8:9], v[126:127] op_sel_hi:[1,0]
	v_pk_mul_f32 v[10:11], v[10:11], v[126:127] op_sel_hi:[1,0]
	v_fmamk_f32 v126, v212, 0x3a800000, v223
	v_rsq_f32_e32 v126, v126
	s_nop 0
	v_pk_mul_f32 v[68:69], v[68:69], v[126:127] op_sel_hi:[1,0]
	v_pk_mul_f32 v[70:71], v[70:71], v[126:127] op_sel_hi:[1,0]
	v_pk_mul_f32 v[4:5], v[4:5], v[126:127] op_sel_hi:[1,0]
	v_pk_mul_f32 v[6:7], v[6:7], v[126:127] op_sel_hi:[1,0]
	v_pk_mul_f32 v[64:65], v[64:65], v[126:127] op_sel_hi:[1,0]
	v_pk_mul_f32 v[66:67], v[66:67], v[126:127] op_sel_hi:[1,0]
	v_pk_mul_f32 v[0:1], v[0:1], v[126:127] op_sel_hi:[1,0]
	v_pk_mul_f32 v[2:3], v[2:3], v[126:127] op_sel_hi:[1,0]
	v_fmamk_f32 v126, v213, 0x3a800000, v223
	v_rsq_f32_e32 v126, v126
	s_nop 0
	v_pk_mul_f32 v[122:123], v[122:123], v[126:127] op_sel_hi:[1,0]
	v_pk_mul_f32 v[124:125], v[124:125], v[126:127] op_sel_hi:[1,0]
	v_pk_mul_f32 v[16:17], v[16:17], v[126:127] op_sel_hi:[1,0]
	v_pk_mul_f32 v[18:19], v[18:19], v[126:127] op_sel_hi:[1,0]
	v_pk_mul_f32 v[128:129], v[128:129], v[126:127] op_sel_hi:[1,0]
	v_pk_mul_f32 v[130:131], v[130:131], v[126:127] op_sel_hi:[1,0]
	v_pk_mul_f32 v[20:21], v[20:21], v[126:127] op_sel_hi:[1,0]
	v_pk_mul_f32 v[22:23], v[22:23], v[126:127] op_sel_hi:[1,0]
	s_and_saveexec_b64 s[20:21], s[50:51]
	s_cbranch_execz .Lmy_p5_xw
	ds_write_b128 v189, v[140:143]
	ds_write_b128 v189, v[114:117] offset:16
	ds_write_b128 v189, v[36:39] offset:32
	ds_write_b128 v189, v[32:35] offset:48
	ds_write_b128 v189, v[152:155] offset:64
	ds_write_b128 v189, v[148:151] offset:80
	ds_write_b128 v189, v[48:51] offset:96
	ds_write_b128 v189, v[44:47] offset:112
	ds_write_b128 v189, v[68:71] offset:4096
	ds_write_b128 v189, v[64:67] offset:4112
	ds_write_b128 v189, v[4:7] offset:4128
	ds_write_b128 v189, v[0:3] offset:4144
	ds_write_b128 v189, v[122:125] offset:4160
	ds_write_b128 v189, v[128:131] offset:4176
	ds_write_b128 v189, v[16:19] offset:4192
	ds_write_b128 v189, v[20:23] offset:4208

; #define LAS __attribute__((address_space(3)))
;     __device__ __forceinline__ void operator()(AccT& acc, const Unit& u, int wr, int wc, int fr, int fq) const {
;     ...
;         for (int n = 0; n < 2; ++n) {
;             const int colg = colg0 + n * 4, colv = FF + colg;
;             if (n == 1) {
; #pragma unroll
;                 for (int j = 0; j < 3; ++j) { cwg[1][j] = *(const f32x4*)(cw + j * FF2 + colg); cwv[1][j] = *(const f32x4*)(cw + j * FF2 + colv); }
;                 cbg[1] = *(const f32x4*)(cb + colg); cbv[1] = *(const f32x4*)(cb + colv); }
;             const f32x4 w0g = cwg[n][0], w1g = cwg[n][1], w2g = cwg[n][2], bg = cbg[n];
;             const f32x4 w0v = cwv[n][0], w1v = cwv[n][1], w2v = cwv[n][2], bv = cbv[n];
; #pragma unroll
;             for (int ai = 0; ai < 2; ++ai) {
;                 f32x4 hg = (f32x4){0.f, 0.f, 0.f, 0.f}, hv = hg;
;                 const int s = ai * 2 + wr;
;                 if (s > 0 && fr >= 14) {
;                     hg = *(const LAS f32x4*)(xch + (((s - 1) * 2 + (fr - 14)) * 256 + wc * 32 + fq * 8 + n * 4));
;                     hv = *(const LAS f32x4*)(xch + (((s - 1) * 2 + (fr - 14)) * 256 + 128 + wc * 32 + fq * 8 + n * 4));
;                 }
.Lmy_p5_6:
	s_or_b64 exec, exec, s[22:23]
	ds_read_b128 v[98:101], v255
	ds_read_b128 v[102:105], v255 offset:16
	ds_read_b128 v[106:109], v255 offset:32
	ds_read_b128 v[110:113], v255 offset:48
	ds_read_b128 v[84:87], v255 offset:64
	ds_read_b128 v[92:95], v255 offset:80
	ds_read_b128 v[88:91], v255 offset:96
	ds_read_b128 v[80:83], v255 offset:112
	s_waitcnt lgkmcnt(0)
	v_mov_b64_e32 v[164:165], 0
	v_mov_b64_e32 v[166:167], 0
	v_mov_b64_e32 v[168:169], 0
	v_mov_b64_e32 v[170:171], 0
	v_mov_b64_e32 v[234:235], 0
	v_mov_b64_e32 v[236:237], 0
	v_mov_b64_e32 v[250:251], 0
	v_mov_b64_e32 v[252:253], 0
	s_and_saveexec_b64 s[20:21], s[80:81]
	s_cbranch_execz .Lmy_p5_7
	ds_read_b128 v[234:237], v188 offset:32
	ds_read_b128 v[250:253], v188 offset:48
	ds_read_b128 v[164:167], v188 offset:96
	ds_read_b128 v[168:171], v188 offset:112
